# attention fast steps: row-max lane exchange only in the rare reference-raise block; common path tests each lane's own max
# baseline (speedup 1.0000x reference)
; __device__ void attn_item(const Params& p, char* lds, int bh, int qi) {
;     ...
;     S0 = __builtin_amdgcn_mfma_f32_32x32x16_bf16(*(const bf16x8*)(ks_), qf[0], cb, 0, 0, 0);
; #pragma unroll
;     for (int ks = 1; ks < 4; ++ks) S0 = __builtin_amdgcn_mfma_f32_32x32x16_bf16(*(const bf16x8*)(ks_ + ks * 16), qf[ks], S0, 0, 0, 0);
;     S1 = __builtin_amdgcn_mfma_f32_32x32x16_bf16(*(const bf16x8*)(ks_ + 32 * LD), qf[0], cb, 0, 0, 0);
; #pragma unroll
;     for (int ks = 1; ks < 4; ++ks) S1 = __builtin_amdgcn_mfma_f32_32x32x16_bf16(*(const bf16x8*)(ks_ + 32 * LD + ks * 16), qf[ks], S1, 0, 0, 0);
;     ...
;     float mx0 = -INFINITY, mx1 = -INFINITY, ps0 = 0.f, ps1 = 0.f;
; #pragma unroll
;     for (int r = 0; r < 16; r += 2) mx0 = fmaxf(fmaxf(mx0, S0[r]), S0[r + 1]);
; #pragma unroll
;     for (int r = 0; r < 16; ++r) { S0[r] = __builtin_amdgcn_exp2f(S0[r]); ps0 += S0[r]; }
; #pragma unroll
;     for (int sp = 0; sp < 2; ++sp) {
;       u32x4 pw;
;       pw.x = pk2(S0[8 * sp + 0], S0[8 * sp + 1]); pw.y = pk2(S0[8 * sp + 2], S0[8 * sp + 3]);
;       pw.z = pk2(S0[8 * sp + 4], S0[8 * sp + 5]); pw.w = pk2(S0[8 * sp + 6], S0[8 * sp + 7]);
;       const bf16x8 pb = __builtin_bit_cast(bf16x8, pw);
; #pragma unroll
;       for (int d = 0; d < 2; ++d) O[d] = __builtin_amdgcn_mfma_f32_32x32x16_bf16(*(const bf16x8*)(vs_ + d * 32 * LD + sp * 16), pb, O[d], 0, 0, 0);
;     }
; #pragma unroll
;     for (int r = 0; r < 16; r += 2) mx1 = fmaxf(fmaxf(mx1, S1[r]), S1[r + 1]);
; #pragma unroll
;     for (int r = 0; r < 16; ++r) { S1[r] = __builtin_amdgcn_exp2f(S1[r]); ps1 += S1[r]; }
; #pragma unroll
;     for (int sp = 0; sp < 2; ++sp) {
;       u32x4 pw;
;       pw.x = pk2(S1[8 * sp + 0], S1[8 * sp + 1]); pw.y = pk2(S1[8 * sp + 2], S1[8 * sp + 3]);
;       pw.z = pk2(S1[8 * sp + 4], S1[8 * sp + 5]); pw.w = pk2(S1[8 * sp + 6], S1[8 * sp + 7]);
;       const bf16x8 pb = __builtin_bit_cast(bf16x8, pw);
; #pragma unroll
;       for (int d = 0; d < 2; ++d) O[d] = __builtin_amdgcn_mfma_f32_32x32x16_bf16(*(const bf16x8*)(vs_ + d * 32 * LD + 32 + sp * 16), pb, O[d], 0, 0, 0);
;     }
;     lsum += ps0 + ps1;
;     ...
;     __builtin_amdgcn_sched_group_barrier(0x008, 4, 0);
; #pragma unroll
;     for (int i = 0; i < 4; ++i) { __builtin_amdgcn_sched_group_barrier(0x008, 1, 0); __builtin_amdgcn_sched_group_barrier(0x002, 12, 0); }
; #pragma unroll
.LBB0_436:
	s_and_b32 s26, s6, 64
	s_mulk_i32 s26, 0x90
	v_add_u32_e32 v127, s26, v119
	ds_read_b128 v[90:93], v127 offset:4672
	s_add_i32 s26, s6, 63
	v_cmp_le_u32_e32 vcc, s26, v112
	s_xor_b64 s[22:23], s[22:23], -1
	s_or_b64 s[22:23], s[22:23], vcc
	s_and_saveexec_b64 s[26:27], s[22:23]
	s_xor_b64 s[22:23], exec, s[26:27]
	s_cbranch_execz .LBB0_440
	ds_read_b128 v[128:131], v127
	ds_read_b128 v[132:135], v127 offset:32
	v_cndmask_b32_e64 v50, v125, -v107, s[24:25]
	v_mov_b32_e32 v51, v50
	v_mov_b32_e32 v52, v50
	v_mov_b32_e32 v53, v50
	v_mov_b32_e32 v54, v50
	v_mov_b32_e32 v55, v50
	v_mov_b32_e32 v56, v50
	v_mov_b32_e32 v57, v50
	v_mov_b32_e32 v58, v50
	v_mov_b32_e32 v59, v50
	v_mov_b32_e32 v60, v50
	v_mov_b32_e32 v61, v50
	v_mov_b32_e32 v62, v50
	v_mov_b32_e32 v63, v50
	v_mov_b32_e32 v64, v50
	v_mov_b32_e32 v65, v50
	v_cmp_lt_i32_e32 vcc, v156, v157
	s_waitcnt lgkmcnt(1)
	v_mfma_f32_32x32x16_bf16 v[34:49], v[128:131], v[66:69], v[50:65]
	ds_read_b128 v[128:131], v127 offset:4608
	ds_read_b128 v[136:139], v127 offset:4640
	s_waitcnt lgkmcnt(2)
	v_mfma_f32_32x32x16_bf16 v[34:49], v[132:135], v[70:73], v[34:49]
	s_waitcnt lgkmcnt(1)
	v_mfma_f32_32x32x16_bf16 v[50:65], v[128:131], v[66:69], v[50:65]
	ds_read_b128 v[128:131], v127 offset:64
	ds_read_b128 v[132:135], v127 offset:96
	s_waitcnt lgkmcnt(1)
	v_mfma_f32_32x32x16_bf16 v[34:49], v[128:131], v[74:77], v[34:49]
	ds_read_b128 v[128:131], v127 offset:4704
	v_mfma_f32_32x32x16_bf16 v[50:65], v[136:139], v[70:73], v[50:65]
	s_waitcnt lgkmcnt(1)
	v_mfma_f32_32x32x16_bf16 v[34:49], v[132:135], v[78:81], v[34:49]
	v_mfma_f32_32x32x16_bf16 v[50:65], v[90:93], v[74:77], v[50:65]
	s_nop 10
	v_exp_f32_e32 v140, v34
	v_max_f32_e32 v34, v34, v34
	v_max_f32_e32 v34, 0xff800000, v34
	v_max3_f32 v34, v34, v35, v36
	v_max3_f32 v34, v34, v37, v38
	v_max3_f32 v34, v34, v39, v40
	v_max3_f32 v34, v34, v41, v42
	s_waitcnt lgkmcnt(0)
	v_mfma_f32_32x32x16_bf16 v[50:65], v[128:131], v[78:81], v[50:65]
	v_exp_f32_e32 v142, v35
	v_exp_f32_e32 v144, v36
	v_exp_f32_e32 v146, v37
	v_exp_f32_e32 v148, v38
	v_exp_f32_e32 v150, v39
	v_exp_f32_e32 v152, v40
	v_exp_f32_e32 v154, v41
	v_max3_f32 v34, v34, v43, v44
	v_exp_f32_e32 v158, v42
	v_exp_f32_e32 v160, v43
	v_exp_f32_e32 v162, v44
	v_exp_f32_e32 v164, v45
	v_max3_f32 v34, v34, v45, v46
	ds_read_b128 v[38:41], v127 offset:18432
	ds_read_b128 v[42:45], v127 offset:23040
	v_exp_f32_e32 v170, v48
	v_max3_f32 v48, v34, v47, v48
	v_cvt_pk_bf16_f32 v34, v140, v142
	v_cvt_pk_bf16_f32 v35, v144, v146
	v_cvt_pk_bf16_f32 v36, v148, v150
	v_cvt_pk_bf16_f32 v37, v152, v154
	v_exp_f32_e32 v166, v46
	v_max3_f32 v46, v50, s34, v51
	s_waitcnt lgkmcnt(1)
	v_mfma_f32_32x32x16_bf16 v[18:33], v[38:41], v[34:37], v[18:33]
	v_max3_f32 v46, v46, v52, v53
	v_exp_f32_e32 v141, v50
	v_max3_f32 v38, v46, v54, v55
	v_exp_f32_e32 v143, v51
	v_exp_f32_e32 v168, v47
	v_exp_f32_e32 v172, v49
	v_max3_f32 v38, v38, v56, v57
	s_waitcnt lgkmcnt(0)
	v_mfma_f32_32x32x16_bf16 v[2:17], v[42:45], v[34:37], v[2:17]
	v_exp_f32_e32 v145, v52
	ds_read_b128 v[128:131], v127 offset:18464
	ds_read_b128 v[132:135], v127 offset:23072
	v_max3_f32 v38, v38, v58, v59
	v_exp_f32_e32 v147, v53
	v_max3_f32 v38, v38, v60, v61
	v_pk_add_f32 v[34:35], v[140:141], 0 op_sel_hi:[1,0]
	v_max3_f32 v38, v38, v62, v63
	v_pk_add_f32 v[42:43], v[142:143], v[34:35]
	v_cvt_pk_bf16_f32 v90, v158, v160
	v_cvt_pk_bf16_f32 v91, v162, v164
	v_cvt_pk_bf16_f32 v92, v166, v168
	v_cvt_pk_bf16_f32 v93, v170, v172
	v_max3_f32 v136, v38, v64, v65
	ds_read_b128 v[38:41], v127 offset:18528
	ds_read_b128 v[34:37], v127 offset:18496
	v_pk_add_f32 v[42:43], v[144:145], v[42:43]
	s_waitcnt lgkmcnt(3)
	v_mfma_f32_32x32x16_bf16 v[18:33], v[128:131], v[90:93], v[18:33]
	v_add_f32_e64 v46, v146, v42
	v_add_f32_e64 v47, v147, v43
	ds_read_b128 v[42:45], v127 offset:23104
	v_exp_f32_e32 v149, v54
	v_exp_f32_e32 v151, v55
	v_exp_f32_e32 v153, v56
	v_exp_f32_e32 v155, v57
	v_cvt_pk_bf16_f32 v50, v141, v143
	s_waitcnt lgkmcnt(3)
	v_mfma_f32_32x32x16_bf16 v[2:17], v[132:135], v[90:93], v[2:17]
	v_cvt_pk_bf16_f32 v51, v145, v147
	v_cvt_pk_bf16_f32 v52, v149, v151
	v_cvt_pk_bf16_f32 v53, v153, v155
	v_exp_f32_e32 v159, v58
	v_exp_f32_e32 v161, v59
	v_exp_f32_e32 v163, v60
	v_exp_f32_e32 v165, v61
	s_waitcnt lgkmcnt(1)
	v_mfma_f32_32x32x16_bf16 v[18:33], v[34:37], v[50:53], v[18:33]
	v_exp_f32_e32 v167, v62
	v_exp_f32_e32 v169, v63
	v_exp_f32_e32 v171, v64
	v_exp_f32_e32 v173, v65
	v_pk_add_f32 v[46:47], v[148:149], v[46:47]
	v_cvt_pk_bf16_f32 v34, v159, v161
	v_pk_add_f32 v[46:47], v[150:151], v[46:47]
	s_waitcnt lgkmcnt(0)
	v_mfma_f32_32x32x16_bf16 v[2:17], v[42:45], v[50:53], v[2:17]
	ds_read_b128 v[42:45], v127 offset:23136
	v_add_f32_e64 v46, v152, v46
	v_add_f32_e64 v47, v153, v47
	v_cvt_pk_bf16_f32 v35, v163, v165
	v_cvt_pk_bf16_f32 v36, v167, v169
	v_cvt_pk_bf16_f32 v37, v171, v173
	v_pk_add_f32 v[46:47], v[154:155], v[46:47]
	s_nop 0
	v_mfma_f32_32x32x16_bf16 v[18:33], v[38:41], v[34:37], v[18:33]
	v_add_f32_e64 v38, v158, v46
	v_add_f32_e64 v39, v159, v47
	v_max3_f32 v40, v48, v49, v136
	v_add_f32_e64 v38, v160, v38
	v_add_f32_e64 v39, v161, v39
	v_pk_add_f32 v[38:39], v[162:163], v[38:39]
	s_nop 0
	v_pk_add_f32 v[38:39], v[164:165], v[38:39]
	s_waitcnt lgkmcnt(0)
	v_mfma_f32_32x32x16_bf16 v[2:17], v[42:45], v[34:37], v[2:17]
	v_add_f32_e64 v38, v166, v38
	v_add_f32_e64 v39, v167, v39
	v_pk_add_f32 v[38:39], v[168:169], v[38:39]
	s_nop 0
	v_pk_add_f32 v[34:35], v[170:171], v[38:39]
	s_nop 0
	v_pk_add_f32 v[34:35], v[172:173], v[34:35]
	s_nop 0
	v_add_f32_e32 v34, v34, v35
	v_add_f32_e32 v126, v126, v34
	v_cmp_lt_f32_e32 vcc, s35, v40
	s_cbranch_vccz .LBB0_439
	v_cmp_lt_i32_e32 vcc, v156, v157
	s_nop 1
	v_cndmask_b32_e32 v36, v1, v156, vcc
	v_lshlrev_b32_e32 v36, 2, v36
	ds_bpermute_b32 v36, v36, v40
	s_waitcnt lgkmcnt(0)
	v_max_f32_e32 v34, v36, v36
	v_max_f32_e32 v34, v40, v34
	v_cmp_lt_f32_e32 vcc, s35, v34
	s_nop 1
	s_nop 0
	v_cndmask_b32_e32 v35, 0, v34, vcc
	v_exp_f32_e64 v34, -v35
	v_add_f32_e32 v107, v107, v35
	v_mul_f32_e32 v126, v126, v34
	v_pk_mul_f32 v[32:33], v[32:33], v[34:35] op_sel_hi:[1,0]
	v_pk_mul_f32 v[30:31], v[30:31], v[34:35] op_sel_hi:[1,0]
	v_pk_mul_f32 v[28:29], v[28:29], v[34:35] op_sel_hi:[1,0]
	v_pk_mul_f32 v[26:27], v[26:27], v[34:35] op_sel_hi:[1,0]
	v_pk_mul_f32 v[24:25], v[24:25], v[34:35] op_sel_hi:[1,0]
	v_pk_mul_f32 v[22:23], v[22:23], v[34:35] op_sel_hi:[1,0]
	v_pk_mul_f32 v[20:21], v[20:21], v[34:35] op_sel_hi:[1,0]
	v_pk_mul_f32 v[18:19], v[18:19], v[34:35] op_sel_hi:[1,0]
	v_pk_mul_f32 v[16:17], v[16:17], v[34:35] op_sel_hi:[1,0]
	v_pk_mul_f32 v[14:15], v[14:15], v[34:35] op_sel_hi:[1,0]
	v_pk_mul_f32 v[12:13], v[12:13], v[34:35] op_sel_hi:[1,0]
	v_pk_mul_f32 v[10:11], v[10:11], v[34:35] op_sel_hi:[1,0]
	v_pk_mul_f32 v[8:9], v[8:9], v[34:35] op_sel_hi:[1,0]
	v_pk_mul_f32 v[6:7], v[6:7], v[34:35] op_sel_hi:[1,0]
	v_pk_mul_f32 v[4:5], v[4:5], v[34:35] op_sel_hi:[1,0]
	v_pk_mul_f32 v[2:3], v[2:3], v[34:35] op_sel_hi:[1,0]
; __device__ __forceinline__ int rm32(int reg, int h) { return (reg & 3) + 8 * (reg >> 2) + 4 * h; }
; __device__ void attn_item(const Params& p, char* lds, int bh, int qi) {
;     ...
;     f32x16 cb, S0, S1;
;     {
;       const float cinit = sel ? -mref : -INFINITY;
; #pragma unroll
;       for (int r = 0; r < 16; ++r) cb[r] = cinit;
;     }
;     S0 = __builtin_amdgcn_mfma_f32_32x32x16_bf16(*(const bf16x8*)(ks_), qf[0], cb, 0, 0, 0);
; #pragma unroll
;     for (int ks = 1; ks < 4; ++ks) S0 = __builtin_amdgcn_mfma_f32_32x32x16_bf16(*(const bf16x8*)(ks_ + ks * 16), qf[ks], S0, 0, 0, 0);
;     S1 = __builtin_amdgcn_mfma_f32_32x32x16_bf16(*(const bf16x8*)(ks_ + 32 * LD), qf[0], cb, 0, 0, 0);
; #pragma unroll
;     for (int ks = 1; ks < 4; ++ks) S1 = __builtin_amdgcn_mfma_f32_32x32x16_bf16(*(const bf16x8*)(ks_ + 32 * LD + ks * 16), qf[ks], S1, 0, 0, 0);
;     if constexpr (DIAG) {
;       const int qrel = wave * 32 + l31;
; #pragma unroll
;       for (int r = 0; r < 16; ++r) {
;         const int krel = sub * 64 + rm32(r, h);
;         S0[r] = (krel <= qrel) ? S0[r] : -INFINITY;
;         S1[r] = (krel + 32 <= qrel) ? S1[r] : -INFINITY;
;       }
;     }
;     float mx0 = -INFINITY, mx1 = -INFINITY, ps0 = 0.f, ps1 = 0.f;
; #pragma unroll
;     for (int r = 0; r < 16; r += 2) mx0 = fmaxf(fmaxf(mx0, S0[r]), S0[r + 1]);
; #pragma unroll
;     for (int r = 0; r < 16; ++r) { S0[r] = __builtin_amdgcn_exp2f(S0[r]); ps0 += S0[r]; }
.LBB0_439:
.LBB0_440:
	s_andn2_saveexec_b64 s[22:23], s[22:23]
	s_cbranch_execz .LBB0_443
	ds_read_b128 v[128:131], v127
	ds_read_b128 v[132:135], v127 offset:32
	v_xor_b32_e32 v34, 0x80000000, v107
	v_mov_b32_e32 v35, v34
	v_mov_b32_e32 v36, v34
	v_mov_b32_e32 v37, v34
	v_mov_b32_e32 v38, v34
	v_mov_b32_e32 v39, v34
	v_mov_b32_e32 v40, v34
	v_mov_b32_e32 v41, v34
	v_mov_b32_e32 v42, v34
	v_mov_b32_e32 v43, v34
	v_mov_b32_e32 v44, v34
	v_mov_b32_e32 v45, v34
	v_mov_b32_e32 v46, v34
	v_mov_b32_e32 v47, v34
	v_mov_b32_e32 v48, v34
	v_mov_b32_e32 v49, v34
	s_waitcnt lgkmcnt(1)
	s_nop 0
	v_mfma_f32_32x32x16_bf16 v[50:65], v[128:131], v[66:69], v[34:49]
	ds_read_b128 v[128:131], v127 offset:4608
	ds_read_b128 v[136:139], v127 offset:4640
	s_waitcnt lgkmcnt(1)
	v_mfma_f32_32x32x16_bf16 v[34:49], v[128:131], v[66:69], v[34:49]
	s_waitcnt lgkmcnt(0)
	v_mfma_f32_32x32x16_bf16 v[34:49], v[136:139], v[70:73], v[34:49]
	v_mfma_f32_32x32x16_bf16 v[50:65], v[132:135], v[70:73], v[50:65]
	v_add_u32_e32 v132, s6, v120
	v_cmp_le_u32_e32 vcc, v132, v113
	v_add_u32_e32 v133, 32, v132
	v_mfma_f32_32x32x16_bf16 v[34:49], v[90:93], v[74:77], v[34:49]
	ds_read_b128 v[90:93], v127 offset:64
	ds_read_b128 v[128:131], v127 offset:96
	s_waitcnt lgkmcnt(1)
	v_mfma_f32_32x32x16_bf16 v[50:65], v[90:93], v[74:77], v[50:65]
	ds_read_b128 v[90:93], v127 offset:4704
	s_waitcnt lgkmcnt(1)
	v_mfma_f32_32x32x16_bf16 v[50:65], v[128:131], v[78:81], v[50:65]
	ds_read_b128 v[128:131], v127 offset:18432
	s_waitcnt lgkmcnt(1)
	v_mfma_f32_32x32x16_bf16 v[34:49], v[90:93], v[78:81], v[34:49]
	s_nop 8
	v_cndmask_b32_e32 v50, v125, v50, vcc
	v_cmp_le_u32_e32 vcc, v133, v113
	s_nop 1
	v_cndmask_b32_e32 v90, v125, v34, vcc
	v_cmp_lt_u32_e32 vcc, v132, v113
	s_nop 1
	v_cndmask_b32_e32 v34, v125, v51, vcc
	v_add_u32_e32 v51, 33, v132
	v_cmp_le_u32_e32 vcc, v51, v113
	v_add_u32_e32 v51, 34, v132
	s_nop 0
	v_cndmask_b32_e32 v92, v125, v35, vcc
	v_add_u32_e32 v35, 2, v132
	v_cmp_le_u32_e32 vcc, v35, v113
	s_nop 1
	v_cndmask_b32_e32 v35, v125, v52, vcc
	v_cmp_le_u32_e32 vcc, v51, v113
	s_nop 1
	v_cndmask_b32_e32 v134, v125, v36, vcc
	v_add_u32_e32 v36, 3, v132
	v_cmp_le_u32_e32 vcc, v36, v113
	v_add_u32_e32 v36, 35, v132
	s_nop 0
	v_cndmask_b32_e32 v136, v125, v53, vcc
	v_cmp_le_u32_e32 vcc, v36, v113
	v_add_u32_e32 v36, 8, v132
	s_nop 0
	v_cndmask_b32_e32 v138, v125, v37, vcc
	v_cmp_le_u32_e32 vcc, v36, v113
	v_add_u32_e32 v36, 40, v132
	s_nop 0
	v_cndmask_b32_e32 v54, v125, v54, vcc
	v_cmp_le_u32_e32 vcc, v36, v113
	v_add_u32_e32 v36, 9, v132
	s_nop 0
	v_cndmask_b32_e32 v140, v125, v38, vcc
	v_cmp_le_u32_e32 vcc, v36, v113
	v_add_u32_e32 v36, 41, v132
	s_nop 0
	v_cndmask_b32_e32 v142, v125, v55, vcc
	v_cmp_le_u32_e32 vcc, v36, v113
	v_add_u32_e32 v36, 10, v132
	v_exp_f32_e32 v55, v50
	v_cndmask_b32_e32 v144, v125, v39, vcc
	v_cmp_le_u32_e32 vcc, v36, v113
	v_add_u32_e32 v36, 42, v132
	s_nop 0
	v_cndmask_b32_e32 v56, v125, v56, vcc
	v_cmp_le_u32_e32 vcc, v36, v113
	v_add_u32_e32 v36, 11, v132
	v_exp_f32_e32 v91, v56
	v_cndmask_b32_e32 v145, v125, v40, vcc
	v_cmp_le_u32_e32 vcc, v36, v113
	v_add_u32_e32 v36, 43, v132
	s_nop 0
	v_cndmask_b32_e32 v146, v125, v57, vcc
	v_cmp_le_u32_e32 vcc, v36, v113
	v_add_u32_e32 v36, 16, v132
	v_exp_f32_e32 v57, v34
	v_cndmask_b32_e32 v147, v125, v41, vcc
	v_cmp_le_u32_e32 vcc, v36, v113
	v_add_u32_e32 v36, 48, v132
	ds_read_b128 v[38:41], v127 offset:23040
	v_cndmask_b32_e32 v58, v125, v58, vcc
	v_cmp_le_u32_e32 vcc, v36, v113
	v_add_u32_e32 v36, 17, v132
	v_exp_f32_e32 v93, v146
	v_cndmask_b32_e32 v148, v125, v42, vcc
	v_cmp_le_u32_e32 vcc, v36, v113
	v_add_u32_e32 v36, 49, v132
	v_cvt_pk_bf16_f32 v37, v91, v93
	v_cndmask_b32_e32 v149, v125, v59, vcc
	v_cmp_le_u32_e32 vcc, v36, v113
	v_add_u32_e32 v36, 18, v132
	v_exp_f32_e32 v59, v35
	v_cndmask_b32_e32 v150, v125, v43, vcc
	v_cmp_le_u32_e32 vcc, v36, v113
	v_add_u32_e32 v36, 50, v132
	v_exp_f32_e32 v133, v58
	v_cndmask_b32_e32 v60, v125, v60, vcc
	v_cmp_le_u32_e32 vcc, v36, v113
	v_add_u32_e32 v36, 19, v132
	v_exp_f32_e32 v135, v149
	v_cndmask_b32_e32 v151, v125, v44, vcc
	v_cmp_le_u32_e32 vcc, v36, v113
	v_add_u32_e32 v36, 51, v132
	s_nop 0
	v_cndmask_b32_e32 v152, v125, v61, vcc
	v_cmp_le_u32_e32 vcc, v36, v113
	v_add_u32_e32 v36, 24, v132
	v_exp_f32_e32 v61, v136
	v_cndmask_b32_e32 v153, v125, v45, vcc
	v_cmp_le_u32_e32 vcc, v36, v113
	v_add_u32_e32 v36, 56, v132
	s_nop 0
	v_cndmask_b32_e32 v62, v125, v62, vcc
	v_cmp_le_u32_e32 vcc, v36, v113
	v_add_u32_e32 v36, 25, v132
	v_exp_f32_e32 v137, v62
	v_cndmask_b32_e32 v154, v125, v46, vcc
	v_cmp_le_u32_e32 vcc, v36, v113
	v_add_u32_e32 v36, 57, v132
	s_nop 0
	v_cndmask_b32_e32 v155, v125, v63, vcc
	v_cmp_le_u32_e32 vcc, v36, v113
	v_add_u32_e32 v36, 26, v132
	v_exp_f32_e32 v63, v54
	v_cndmask_b32_e32 v158, v125, v47, vcc
	v_cmp_le_u32_e32 vcc, v36, v113
	v_add_u32_e32 v36, 58, v132
	v_exp_f32_e32 v139, v155
	v_cndmask_b32_e32 v64, v125, v64, vcc
	v_cmp_le_u32_e32 vcc, v36, v113
	v_add_u32_e32 v36, 27, v132
	v_exp_f32_e32 v141, v64
	v_cndmask_b32_e32 v159, v125, v48, vcc
	v_cmp_le_u32_e32 vcc, v36, v113
	v_add_u32_e32 v36, 59, v132
	s_nop 0
	v_cndmask_b32_e32 v160, v125, v65, vcc
	v_exp_f32_e32 v65, v142
	v_cmp_le_u32_e32 vcc, v36, v113
	v_max_f32_e32 v36, v50, v50
	v_max_f32_e32 v36, 0xff800000, v36
	v_max3_f32 v132, v36, v34, v35
	v_cvt_pk_bf16_f32 v34, v55, v57
	v_cvt_pk_bf16_f32 v35, v59, v61
	v_cvt_pk_bf16_f32 v36, v63, v65
	v_exp_f32_e32 v143, v160
	v_cndmask_b32_e32 v161, v125, v49, vcc
	s_waitcnt lgkmcnt(1)
; __device__ __forceinline__ unsigned pk2(float lo, float hi) { f32x2_t v = {lo, hi}; bf16x2_t b = __builtin_convertvector(v, bf16x2_t); return __builtin_bit_cast(unsigned, b); }
; __device__ void attn_item(const Params& p, char* lds, int bh, int qi) {
;     ...
;     for (int sp = 0; sp < 2; ++sp) {
;       u32x4 pw;
;       pw.x = pk2(S0[8 * sp + 0], S0[8 * sp + 1]); pw.y = pk2(S0[8 * sp + 2], S0[8 * sp + 3]);
;       pw.z = pk2(S0[8 * sp + 4], S0[8 * sp + 5]); pw.w = pk2(S0[8 * sp + 6], S0[8 * sp + 7]);
;       const bf16x8 pb = __builtin_bit_cast(bf16x8, pw);
; #pragma unroll
;       for (int d = 0; d < 2; ++d) O[d] = __builtin_amdgcn_mfma_f32_32x32x16_bf16(*(const bf16x8*)(vs_ + d * 32 * LD + sp * 16), pb, O[d], 0, 0, 0);
;     }
; #pragma unroll
;     for (int r = 0; r < 16; r += 2) mx1 = fmaxf(fmaxf(mx1, S1[r]), S1[r + 1]);
; #pragma unroll
;     for (int r = 0; r < 16; ++r) { S1[r] = __builtin_amdgcn_exp2f(S1[r]); ps1 += S1[r]; }
; #pragma unroll
;     for (int sp = 0; sp < 2; ++sp) {
;       u32x4 pw;
;       pw.x = pk2(S1[8 * sp + 0], S1[8 * sp + 1]); pw.y = pk2(S1[8 * sp + 2], S1[8 * sp + 3]);
;       pw.z = pk2(S1[8 * sp + 4], S1[8 * sp + 5]); pw.w = pk2(S1[8 * sp + 6], S1[8 * sp + 7]);
;       const bf16x8 pb = __builtin_bit_cast(bf16x8, pw);
; #pragma unroll
;       for (int d = 0; d < 2; ++d) O[d] = __builtin_amdgcn_mfma_f32_32x32x16_bf16(*(const bf16x8*)(vs_ + d * 32 * LD + 32 + sp * 16), pb, O[d], 0, 0, 0);
;     }
;     lsum += ps0 + ps1;
;     ...
;     __builtin_amdgcn_sched_group_barrier(0x008, 4, 0);
; #pragma unroll
;     for (int i = 0; i < 4; ++i) { __builtin_amdgcn_sched_group_barrier(0x008, 1, 0); __builtin_amdgcn_sched_group_barrier(0x002, 12, 0); }
; #pragma unroll
;     for (int i = 0; i < 4; ++i) { __builtin_amdgcn_sched_group_barrier(0x008, 1, 0); __builtin_amdgcn_sched_group_barrier(0x002, 12, 0); }
;     __builtin_amdgcn_sched_group_barrier(0x008, 4, 0);
;     ...
;     float mx = fmaxf(mx0, mx1);
;     mx = fmaxf(mx, __shfl_xor(mx, 32));
;     if (__ballot(mx > 8.f) != 0ull) {
;       const float delta = (mx > 8.f) ? mx : 0.f;
;       const float alpha = __builtin_amdgcn_exp2f(-delta);
;       mref += delta;
;       lsum *= alpha;
; #pragma unroll
;       for (int d = 0; d < 2; ++d)
; #pragma unroll
;         for (int r = 0; r < 16; ++r) O[d][r] *= alpha;
;     }
	v_mfma_f32_32x32x16_bf16 v[18:33], v[128:131], v[34:37], v[18:33]
	v_exp_f32_e32 v129, v60
	v_exp_f32_e32 v131, v152
	ds_read_b128 v[42:45], v127 offset:18464
	ds_read_b128 v[46:49], v127 offset:18528
	v_exp_f32_e32 v128, v151
	v_exp_f32_e32 v130, v153
	v_cmp_lt_i32_e32 vcc, v156, v157
	s_waitcnt lgkmcnt(2)
	v_mfma_f32_32x32x16_bf16 v[2:17], v[38:41], v[34:37], v[2:17]
	ds_read_b128 v[38:41], v127 offset:23072
	ds_read_b128 v[50:53], v127 offset:18496
	v_cvt_pk_bf16_f32 v34, v133, v135
	v_cvt_pk_bf16_f32 v35, v129, v131
	v_cvt_pk_bf16_f32 v36, v137, v139
	v_cvt_pk_bf16_f32 v37, v141, v143
	s_waitcnt lgkmcnt(3)
	s_nop 0
	v_mfma_f32_32x32x16_bf16 v[18:33], v[42:45], v[34:37], v[18:33]
	v_max3_f32 v42, v132, v136, v54
	v_exp_f32_e32 v54, v90
	v_max3_f32 v42, v42, v142, v56
	v_exp_f32_e32 v56, v92
	v_max3_f32 v42, v42, v146, v58
	v_exp_f32_e32 v58, v134
	v_max3_f32 v42, v42, v149, v60
	s_waitcnt lgkmcnt(1)
	v_mfma_f32_32x32x16_bf16 v[2:17], v[38:41], v[34:37], v[2:17]
	v_max3_f32 v34, v90, s34, v92
	v_max3_f32 v34, v34, v134, v138
	v_max3_f32 v34, v34, v140, v144
	v_max3_f32 v34, v34, v145, v147
	v_max3_f32 v34, v34, v148, v150
	v_max3_f32 v34, v34, v151, v153
	v_exp_f32_e32 v60, v138
	v_max3_f32 v42, v42, v152, v62
	v_max3_f32 v149, v34, v154, v158
	v_pk_add_f32 v[34:35], v[54:55], 0 op_sel_hi:[1,0]
	v_exp_f32_e32 v62, v140
	v_max3_f32 v146, v42, v155, v64
	v_pk_add_f32 v[34:35], v[56:57], v[34:35]
	v_exp_f32_e32 v64, v144
	v_pk_add_f32 v[34:35], v[58:59], v[34:35]
	v_exp_f32_e32 v90, v145
	v_pk_add_f32 v[34:35], v[60:61], v[34:35]
	v_exp_f32_e32 v92, v147
	ds_read_b128 v[42:45], v127 offset:23104
	v_exp_f32_e32 v132, v148
	v_pk_add_f32 v[34:35], v[62:63], v[34:35]
	v_exp_f32_e32 v134, v150
	v_pk_add_f32 v[38:39], v[64:65], v[34:35]
	v_exp_f32_e32 v136, v154
	v_pk_add_f32 v[38:39], v[90:91], v[38:39]
	v_exp_f32_e32 v138, v158
	v_pk_add_f32 v[38:39], v[92:93], v[38:39]
	v_cvt_pk_bf16_f32 v34, v54, v56
	v_pk_add_f32 v[38:39], v[132:133], v[38:39]
	v_cvt_pk_bf16_f32 v35, v58, v60
	v_pk_add_f32 v[38:39], v[134:135], v[38:39]
	v_cvt_pk_bf16_f32 v36, v62, v64
	v_pk_add_f32 v[38:39], v[128:129], v[38:39]
	v_cvt_pk_bf16_f32 v37, v90, v92
	v_pk_add_f32 v[38:39], v[130:131], v[38:39]
	v_exp_f32_e32 v140, v159
	v_pk_add_f32 v[38:39], v[136:137], v[38:39]
	s_waitcnt lgkmcnt(1)
	v_mfma_f32_32x32x16_bf16 v[18:33], v[50:53], v[34:37], v[18:33]
	v_exp_f32_e32 v142, v161
	s_waitcnt lgkmcnt(0)
	v_mfma_f32_32x32x16_bf16 v[2:17], v[42:45], v[34:37], v[2:17]
	v_add_f32_e64 v34, v138, v38
	v_add_f32_e64 v35, v139, v39
	ds_read_b128 v[38:41], v127 offset:23136
	v_max3_f32 v44, v149, v159, v161
	v_pk_add_f32 v[42:43], v[140:141], v[34:35]
	v_cvt_pk_bf16_f32 v34, v132, v134
	v_cvt_pk_bf16_f32 v35, v128, v130
	v_cvt_pk_bf16_f32 v36, v136, v138
	v_cvt_pk_bf16_f32 v37, v140, v142
	v_max3_f32 v44, v146, v160, v44
	v_mfma_f32_32x32x16_bf16 v[18:33], v[46:49], v[34:37], v[18:33]
	v_add_f32_e64 v42, v142, v42
	v_add_f32_e64 v43, v143, v43
	s_waitcnt lgkmcnt(0)
	v_mfma_f32_32x32x16_bf16 v[2:17], v[38:41], v[34:37], v[2:17]
	v_add_f32_e32 v34, v42, v43
	v_add_f32_e32 v126, v126, v34
	v_cmp_lt_f32_e32 vcc, s35, v44
	s_cbranch_vccz .LBB0_443
	v_cmp_lt_i32_e32 vcc, v156, v157
	s_nop 1
	v_cndmask_b32_e32 v45, v1, v156, vcc
	v_lshlrev_b32_e32 v45, 2, v45
	ds_bpermute_b32 v45, v45, v44
	s_waitcnt lgkmcnt(0)
	v_max_f32_e32 v34, v45, v45
	v_max_f32_e32 v34, v44, v34
	v_cmp_lt_f32_e32 vcc, s35, v34
	s_nop 1
	s_nop 0
	v_cndmask_b32_e32 v35, 0, v34, vcc
	v_exp_f32_e64 v34, -v35
	v_add_f32_e32 v107, v107, v35
	v_mul_f32_e32 v126, v126, v34
	v_pk_mul_f32 v[32:33], v[32:33], v[34:35] op_sel_hi:[1,0]
	v_pk_mul_f32 v[30:31], v[30:31], v[34:35] op_sel_hi:[1,0]
	v_pk_mul_f32 v[28:29], v[28:29], v[34:35] op_sel_hi:[1,0]
	v_pk_mul_f32 v[26:27], v[26:27], v[34:35] op_sel_hi:[1,0]
	v_pk_mul_f32 v[24:25], v[24:25], v[34:35] op_sel_hi:[1,0]
	v_pk_mul_f32 v[22:23], v[22:23], v[34:35] op_sel_hi:[1,0]
	v_pk_mul_f32 v[20:21], v[20:21], v[34:35] op_sel_hi:[1,0]
	v_pk_mul_f32 v[18:19], v[18:19], v[34:35] op_sel_hi:[1,0]
	v_pk_mul_f32 v[16:17], v[16:17], v[34:35] op_sel_hi:[1,0]
	v_pk_mul_f32 v[14:15], v[14:15], v[34:35] op_sel_hi:[1,0]
	v_pk_mul_f32 v[12:13], v[12:13], v[34:35] op_sel_hi:[1,0]
	v_pk_mul_f32 v[10:11], v[10:11], v[34:35] op_sel_hi:[1,0]
	v_pk_mul_f32 v[8:9], v[8:9], v[34:35] op_sel_hi:[1,0]
	v_pk_mul_f32 v[6:7], v[6:7], v[34:35] op_sel_hi:[1,0]
	v_pk_mul_f32 v[4:5], v[4:5], v[34:35] op_sel_hi:[1,0]
	v_pk_mul_f32 v[2:3], v[2:3], v[34:35] op_sel_hi:[1,0]
